# final RMSNorm phase: gain row loaded once, next row's 8 chunks + sumsq prefetched while the current row is scaled and stored
# speedup vs baseline: 1.0035x; 1.0035x over previous
.LBB0_1674:
	s_or_b64 exec, exec, s[0:1]
	v_readlane_b32 s0, v255, 26
	v_readlane_b32 s1, v255, 27
	s_and_b64 vcc, exec, s[0:1]
	s_waitcnt lgkmcnt(0)
	s_barrier
	v_mbcnt_lo_u32_b32 v0, -1, 0
	v_mbcnt_hi_u32_b32 v0, -1, v0
	s_cbranch_vccnz .LBB0_1677
	v_and_b32_e32 v0, 63, v0
	v_lshlrev_b32_e32 v0, 4, v0
	v_mov_b32_e32 v1, 0
	v_lshl_add_u64 v[2:3], s[24:25], 0, v[0:1]
	s_mov_b64 s[2:3], 0x1400
	v_lshl_add_u64 v[6:7], v[2:3], 0, s[2:3]
	s_mov_b64 s[2:3], 0x1800
	s_add_i32 s6, s84, s86
	v_lshl_add_u64 v[8:9], v[2:3], 0, s[2:3]
	s_mov_b64 s[2:3], 0x1c00
	s_ashr_i32 s7, s6, 31
	v_lshl_add_u64 v[10:11], v[2:3], 0, s[2:3]
	s_lshl_b64 s[2:3], s[6:7], 2
	s_add_u32 s2, s28, s2
	s_addc_u32 s3, s29, s3
	s_add_u32 s2, s2, 0xc670000
	s_addc_u32 s3, s3, 0
	s_ashr_i32 s23, s22, 31
	s_lshl_b64 s[4:5], s[22:23], 2
	s_lshl_b64 s[6:7], s[6:7], 13
	s_add_u32 s6, s26, s6
	s_addc_u32 s7, s27, s7
	s_mov_b64 s[0:1], 0x1000
	v_lshl_add_u64 v[12:13], s[6:7], 0, v[0:1]
	v_lshl_add_u64 v[4:5], v[2:3], 0, s[0:1]
	v_lshl_add_u64 v[12:13], v[12:13], 0, s[0:1]
	s_lshl_b64 s[6:7], s[22:23], 13
	v_mov_b32_e32 v0, 0x358637bd
	s_mov_b32 s8, 0xf800000
	v_mov_b32_e32 v14, 0x260
	global_load_dwordx4 v[100:103], v[2:3], off
	global_load_dwordx4 v[104:107], v[2:3], off offset:1024
	global_load_dwordx4 v[108:111], v[2:3], off offset:2048
	global_load_dwordx4 v[112:115], v[2:3], off offset:3072
	global_load_dwordx4 v[116:119], v[4:5], off
	global_load_dwordx4 v[120:123], v[6:7], off
	global_load_dwordx4 v[124:127], v[8:9], off
	global_load_dwordx4 v[128:131], v[10:11], off
	global_load_dword v99, v1, s[2:3]
	s_add_u32 s2, s2, s4
	s_addc_u32 s3, s3, s5
	global_load_dwordx4 v[64:67], v[12:13], off offset:-4096
	global_load_dwordx4 v[68:71], v[12:13], off offset:-3072
	global_load_dwordx4 v[72:75], v[12:13], off offset:-2048
	global_load_dwordx4 v[76:79], v[12:13], off offset:-1024
	global_load_dwordx4 v[80:83], v[12:13], off
	global_load_dwordx4 v[84:87], v[12:13], off offset:1024
	global_load_dwordx4 v[88:91], v[12:13], off offset:2048
	global_load_dwordx4 v[92:95], v[12:13], off offset:3072
	s_waitcnt vmcnt(0)
.LBB0_1676:
	s_mov_b64 s[12:13], s[2:3]
	s_add_u32 s2, s2, s4
	s_addc_u32 s3, s3, s5
	s_add_i32 s33, s33, s22
	s_cmp_lt_i32 s33, 0x8000
	s_cselect_b32 s10, s6, 0
	s_cselect_b32 s11, s7, 0
	s_waitcnt vmcnt(16)
	v_mov_b32_e32 v15, v99
	v_lshl_add_u64 v[96:97], v[12:13], 0, s[10:11]
	v_fmamk_f32 v15, v15, 0x3a000000, v0
	v_mul_f32_e32 v28, 0x4f800000, v15
	v_cmp_gt_f32_e32 vcc, s8, v15
	s_nop 1
	v_cndmask_b32_e32 v15, v15, v28, vcc
	v_sqrt_f32_e32 v28, v15
	s_nop 0
	v_add_u32_e32 v29, -1, v28
	v_add_u32_e32 v30, 1, v28
	v_fma_f32 v31, -v29, v28, v15
	v_fma_f32 v32, -v30, v28, v15
	v_cmp_ge_f32_e64 s[0:1], 0, v31
	s_nop 1
	v_cndmask_b32_e64 v28, v28, v29, s[0:1]
	v_cmp_lt_f32_e64 s[0:1], 0, v32
	s_nop 1
	v_cndmask_b32_e64 v28, v28, v30, s[0:1]
	v_mul_f32_e32 v29, 0x37800000, v28
	v_cndmask_b32_e32 v28, v28, v29, vcc
	v_cmp_class_f32_e32 vcc, v15, v14
	s_nop 1
	v_cndmask_b32_e32 v15, v28, v15, vcc
	v_div_scale_f32 v28, s[0:1], v15, v15, 1.0
	v_rcp_f32_e32 v30, v28
	v_div_scale_f32 v29, vcc, 1.0, v15, 1.0
	v_fma_f32 v31, -v28, v30, 1.0
	v_fmac_f32_e32 v30, v31, v30
	v_mul_f32_e32 v31, v29, v30
	v_fma_f32 v32, -v28, v31, v29
	v_fmac_f32_e32 v31, v32, v30
	v_fma_f32 v28, -v28, v31, v29
	v_div_fmas_f32 v28, v28, v30, v31
	v_div_fixup_f32 v28, v28, v15, 1.0
	global_load_dword v99, v1, s[12:13]
	s_waitcnt vmcnt(15)
	v_pk_mul_f32 v[64:65], v[64:65], v[28:29] op_sel_hi:[1,0]
	v_pk_mul_f32 v[66:67], v[66:67], v[28:29] op_sel_hi:[1,0]
	v_pk_mul_f32 v[64:65], v[100:101], v[64:65]
	v_pk_mul_f32 v[66:67], v[102:103], v[66:67]
	global_store_dwordx4 v[12:13], v[64:67], off offset:-4096
	global_load_dwordx4 v[64:67], v[96:97], off offset:-4096
	s_waitcnt vmcnt(15)
	v_pk_mul_f32 v[68:69], v[68:69], v[28:29] op_sel_hi:[1,0]
	v_pk_mul_f32 v[70:71], v[70:71], v[28:29] op_sel_hi:[1,0]
	v_pk_mul_f32 v[68:69], v[104:105], v[68:69]
	v_pk_mul_f32 v[70:71], v[106:107], v[70:71]
	global_store_dwordx4 v[12:13], v[68:71], off offset:-3072
	global_load_dwordx4 v[68:71], v[96:97], off offset:-3072
	s_waitcnt vmcnt(15)
	v_pk_mul_f32 v[72:73], v[72:73], v[28:29] op_sel_hi:[1,0]
	v_pk_mul_f32 v[74:75], v[74:75], v[28:29] op_sel_hi:[1,0]
	v_pk_mul_f32 v[72:73], v[108:109], v[72:73]
	v_pk_mul_f32 v[74:75], v[110:111], v[74:75]
	global_store_dwordx4 v[12:13], v[72:75], off offset:-2048
	global_load_dwordx4 v[72:75], v[96:97], off offset:-2048
	s_waitcnt vmcnt(15)
	v_pk_mul_f32 v[76:77], v[76:77], v[28:29] op_sel_hi:[1,0]
	v_pk_mul_f32 v[78:79], v[78:79], v[28:29] op_sel_hi:[1,0]
	v_pk_mul_f32 v[76:77], v[112:113], v[76:77]
	v_pk_mul_f32 v[78:79], v[114:115], v[78:79]
	global_store_dwordx4 v[12:13], v[76:79], off offset:-1024
	global_load_dwordx4 v[76:79], v[96:97], off offset:-1024
	s_waitcnt vmcnt(15)
	v_pk_mul_f32 v[80:81], v[80:81], v[28:29] op_sel_hi:[1,0]
	v_pk_mul_f32 v[82:83], v[82:83], v[28:29] op_sel_hi:[1,0]
	v_pk_mul_f32 v[80:81], v[116:117], v[80:81]
	v_pk_mul_f32 v[82:83], v[118:119], v[82:83]
	global_store_dwordx4 v[12:13], v[80:83], off
	global_load_dwordx4 v[80:83], v[96:97], off
	s_waitcnt vmcnt(15)
	v_pk_mul_f32 v[84:85], v[84:85], v[28:29] op_sel_hi:[1,0]
	v_pk_mul_f32 v[86:87], v[86:87], v[28:29] op_sel_hi:[1,0]
	v_pk_mul_f32 v[84:85], v[120:121], v[84:85]
	v_pk_mul_f32 v[86:87], v[122:123], v[86:87]
	global_store_dwordx4 v[12:13], v[84:87], off offset:1024
	global_load_dwordx4 v[84:87], v[96:97], off offset:1024
	s_waitcnt vmcnt(15)
	v_pk_mul_f32 v[88:89], v[88:89], v[28:29] op_sel_hi:[1,0]
	v_pk_mul_f32 v[90:91], v[90:91], v[28:29] op_sel_hi:[1,0]
	v_pk_mul_f32 v[88:89], v[124:125], v[88:89]
	v_pk_mul_f32 v[90:91], v[126:127], v[90:91]
	global_store_dwordx4 v[12:13], v[88:91], off offset:2048
	global_load_dwordx4 v[88:91], v[96:97], off offset:2048
	s_waitcnt vmcnt(15)
	v_pk_mul_f32 v[92:93], v[92:93], v[28:29] op_sel_hi:[1,0]
	v_pk_mul_f32 v[94:95], v[94:95], v[28:29] op_sel_hi:[1,0]
	v_pk_mul_f32 v[92:93], v[128:129], v[92:93]
	v_pk_mul_f32 v[94:95], v[130:131], v[94:95]
	global_store_dwordx4 v[12:13], v[92:95], off offset:3072
	global_load_dwordx4 v[92:95], v[96:97], off offset:3072
	v_mov_b32_e32 v12, v96
	v_mov_b32_e32 v13, v97
	s_cbranch_scc1 .LBB0_1676
.LBB0_1677:
	s_waitcnt vmcnt(0)
	s_endpgm
